# v21_attnkswz
# speedup vs baseline: 1.0265x; 1.0014x over previous
; __device__ __forceinline__ void attn_item(const bf16_t* __restrict__ Q, const bf16_t* __restrict__ Kp, const bf16_t* __restrict__ VT,
;                                           bf16_t* __restrict__ O, int ldo, int nvalid, const float* __restrict__ qn, const float* __restrict__ kn, bf16_t* sm) {
;     ...
;   const int lane = tid & 63, wave = tid >> 6, l15 = lane & 15, quad = lane >> 4;
;   const bool active = (wave * 32 < nvalid);
;   bf16x8 qf[2][4];
; #pragma unroll
;   for (int g = 0; g < 2; ++g)
; #pragma unroll
;     for (int ks = 0; ks < 4; ++ks) qf[g][ks] = *(const bf16x8*)(Q + (size_t)(wave * 32 + g * 16 + l15) * 128 + ks * 32 + quad * 8);
;   f32x4 o[2][8];
; #pragma unroll
;   for (int g = 0; g < 2; ++g)
; #pragma unroll
;     for (int dt = 0; dt < 8; ++dt) o[g][dt] = f32x4{0.f, 0.f, 0.f, 0.f};
;   float l[2] = {0.f, 0.f};
;   const float cscale = 0.08838834764831845f * 1.4426950408889634f;
;   float gq = fmaxf(fabsf(qn[lane]), fabsf(qn[lane + 64])), gk = fmaxf(fabsf(kn[lane]), fabsf(kn[lane + 64]));
; #pragma unroll
;   for (int sft = 32; sft > 0; sft >>= 1) { gq = fmaxf(gq, __shfl_xor(gq, sft)); gk = fmaxf(gk, __shfl_xor(gk, sft)); }
;   const float mc = 11.313708498984761f * gq * gk * 1.4426950408889634f;
;   u32x4 rkA[2], rvA[2], rkB[2], rvB[2];
;   const int krow = tid >> 4, kcc = (tid & 15) * 8;
;   const int vrow = tid >> 3, vcc = (tid & 7) * 8;
;   auto issue = [&](int tile, u32x4 (&rk)[2], u32x4 (&rv)[2]) {
; #pragma unroll
;     for (int i = 0; i < 2; ++i) {
;       rk[i] = *(const u32x4*)(Kp + (size_t)(tile * 64 + krow + 32 * i) * 128 + kcc);
;       rv[i] = *(const u32x4*)(VT + (size_t)(vrow + 64 * i) * LP + tile * 64 + vcc);
;     }
;   };
.LBB0_644:
	s_or_b64 exec, exec, s[6:7]
	v_readlane_b32 s4, v255, 3
	v_mov_b32_e32 v72, v135
	v_readlane_b32 s5, v255, 4
	v_mov_b32_e32 v9, v1
	v_and_b32_e32 v8, 63, v72
	v_lshl_add_u64 v[4:5], v[4:5], 0, s[4:5]
	v_lshlrev_b32_e32 v8, 2, v8
	v_lshl_add_u64 v[6:7], v[6:7], 0, s[4:5]
	v_lshl_add_u64 v[4:5], v[4:5], 0, v[8:9]
	global_load_dword v34, v[4:5], off
	global_load_dword v35, v[4:5], off offset:256
	v_lshl_add_u64 v[4:5], v[6:7], 0, v[8:9]
	s_waitcnt lgkmcnt(0)
	global_load_dword v36, v[4:5], off offset:256
	global_load_dword v37, v[4:5], off
	v_cmp_lt_i32_e32 vcc, v159, v158
	v_sub_u32_e32 v73, 0x810, v0
	v_ashrrev_i32_e32 v24, 4, v72
	v_cndmask_b32_e32 v0, v157, v159, vcc
	v_cmp_lt_i32_e32 vcc, v160, v158
	v_ashrrev_i32_e32 v77, 3, v72
	v_ashrrev_i32_e32 v25, 31, v24
	v_cndmask_b32_e32 v4, v157, v160, vcc
	v_cmp_lt_i32_e32 vcc, v161, v158
	v_lshlrev_b32_e32 v168, 2, v4
	v_ashrrev_i32_e32 v4, 1, v72
	v_cndmask_b32_e32 v5, v157, v161, vcc
	v_cmp_lt_i32_e32 vcc, v162, v158
	v_lshlrev_b32_e32 v155, 2, v0
	v_lshlrev_b32_e32 v52, 2, v5
	v_cndmask_b32_e32 v6, v157, v162, vcc
	v_cmp_lt_i32_e32 vcc, v163, v158
	v_and_b32_e32 v0, 48, v72
	v_lshlrev_b32_e32 v5, 4, v72
	v_cndmask_b32_e32 v7, v157, v163, vcc
	v_and_b32_e32 v78, 0xffffffe0, v4
	v_add_u32_e32 v4, 64, v77
	v_lshlrev_b64 v[18:19], 8, v[24:25]
	v_mov_b32_e32 v21, v1
	v_mov_b32_e32 v23, v1
	v_lshlrev_b32_e32 v74, 2, v6
	v_lshlrev_b32_e32 v75, 2, v7
	v_lshl_add_u64 v[32:33], v[2:3], 0, v[0:1]
	v_and_b32_e32 v20, 0xf0, v5
	v_mad_i64_i32 v[2:3], s[4:5], v77, s66, v[16:17]
	v_and_b32_e32 v22, 0x70, v5
	v_mad_i64_i32 v[6:7], s[4:5], v4, s66, v[16:17]
	v_lshl_add_u64 v[8:9], v[14:15], 0, v[18:19]
	v_lshl_add_u64 v[28:29], v[2:3], 0, v[22:23]
	v_lshl_add_u64 v[26:27], v[6:7], 0, v[22:23]
	v_lshl_add_u64 v[30:31], v[8:9], 0, v[20:21]
	v_and_b32_e32 v76, 15, v72
	v_or_b32_e32 v142, v78, v76
	v_ashrrev_i32_e32 v143, 31, v142
	v_lshlrev_b64 v[10:11], 8, v[142:143]
	s_movk_i32 s4, 0x2000
	v_lshl_add_u64 v[42:43], v[32:33], 0, v[10:11]
	v_add_co_u32_e32 v44, vcc, s4, v30
	global_load_dwordx4 v[2:5], v[28:29], off
	global_load_dwordx4 v[6:9], v[26:27], off
	global_load_dwordx4 v[10:13], v[30:31], off
	v_addc_co_u32_e32 v45, vcc, 0, v31, vcc
	v_or_b32_e32 v140, 16, v142
	v_ashrrev_i32_e32 v141, 31, v140
	v_lshlrev_b64 v[50:51], 8, v[140:141]
	v_lshl_add_u64 v[32:33], v[32:33], 0, v[50:51]
	s_movk_i32 s4, 0x4000
	v_add_co_u32_e32 v70, vcc, s4, v30
	s_movk_i32 s4, 0x6000
	s_nop 0
	v_addc_co_u32_e32 v71, vcc, 0, v31, vcc
	s_movk_i32 s5, 0x110
	v_lshl_or_b32 v18, v76, 4, v18
	v_min_u32_e32 v169, 0x100, v73
	v_cmp_lt_i32_e64 s[6:7], v78, v169
	s_waitcnt vmcnt(6)
	v_max_f32_e64 v23, |v34|, |v34|
	s_waitcnt vmcnt(5)
	v_max_f32_e64 v21, |v35|, |v35|
	s_waitcnt vmcnt(4)
	v_max_f32_e64 v25, |v36|, |v36|
	s_waitcnt vmcnt(3)
	v_max_f32_e64 v34, |v37|, |v37|
	v_max_f32_e32 v21, v23, v21
	v_max_f32_e32 v23, v34, v25
	ds_bpermute_b32 v46, v155, v23
	ds_bpermute_b32 v25, v155, v21
	global_load_dwordx4 v[38:41], v[42:43], off
	global_load_dwordx4 v[34:37], v[42:43], off offset:64
	global_load_dwordx4 v[66:69], v[44:45], off
	s_waitcnt lgkmcnt(1)
	v_max_f32_e32 v44, v46, v46
	v_max_f32_e32 v23, v23, v44
	ds_bpermute_b32 v53, v168, v23
	s_waitcnt lgkmcnt(1)
	v_max_f32_e32 v25, v25, v25
	v_max_f32_e32 v21, v21, v25
	ds_bpermute_b32 v25, v168, v21
	global_load_dwordx4 v[46:49], v[42:43], off offset:128
	s_nop 0
	global_load_dwordx4 v[42:45], v[42:43], off offset:192
	s_waitcnt lgkmcnt(1)
	v_max_f32_e32 v50, v53, v53
	v_max_f32_e32 v23, v23, v50
	ds_bpermute_b32 v79, v52, v23
	s_waitcnt lgkmcnt(1)
	v_max_f32_e32 v25, v25, v25
	v_max_f32_e32 v21, v21, v25
	ds_bpermute_b32 v25, v52, v21
	global_load_dwordx4 v[62:65], v[32:33], off
	global_load_dwordx4 v[58:61], v[32:33], off offset:64
	global_load_dwordx4 v[54:57], v[32:33], off offset:128
	global_load_dwordx4 v[50:53], v[32:33], off offset:192
	s_waitcnt lgkmcnt(1)
	v_max_f32_e32 v32, v79, v79
	v_max_f32_e32 v23, v23, v32
	ds_bpermute_b32 v32, v74, v23
	s_waitcnt lgkmcnt(1)
	v_max_f32_e32 v25, v25, v25
	v_max_f32_e32 v21, v21, v25
	ds_bpermute_b32 v25, v74, v21
	s_waitcnt lgkmcnt(0)
	v_max_f32_e32 v74, v32, v32
	v_add_co_u32_e32 v32, vcc, s4, v30
	s_mov_b32 s4, 0x8000
	s_nop 0
	v_addc_co_u32_e32 v33, vcc, 0, v31, vcc
	s_barrier
; __device__ __forceinline__ void attn_item(const bf16_t* __restrict__ Q, const bf16_t* __restrict__ Kp, const bf16_t* __restrict__ VT,
;                                           bf16_t* __restrict__ O, int ldo, int nvalid, const float* __restrict__ qn, const float* __restrict__ kn, bf16_t* sm) {
;     ...
;   float gq = fmaxf(fabsf(qn[lane]), fabsf(qn[lane + 64])), gk = fmaxf(fabsf(kn[lane]), fabsf(kn[lane + 64]));
; #pragma unroll
;   for (int sft = 32; sft > 0; sft >>= 1) { gq = fmaxf(gq, __shfl_xor(gq, sft)); gk = fmaxf(gk, __shfl_xor(gk, sft)); }
;   const float mc = 11.313708498984761f * gq * gk * 1.4426950408889634f;
;   u32x4 rkA[2], rvA[2], rkB[2], rvB[2];
;   const int krow = tid >> 4, kcc = (tid & 15) * 8;
;   const int vrow = tid >> 3, vcc = (tid & 7) * 8;
;   auto issue = [&](int tile, u32x4 (&rk)[2], u32x4 (&rv)[2]) {
; #pragma unroll
;     for (int i = 0; i < 2; ++i) {
;       rk[i] = *(const u32x4*)(Kp + (size_t)(tile * 64 + krow + 32 * i) * 128 + kcc);
;       rv[i] = *(const u32x4*)(VT + (size_t)(vrow + 64 * i) * LP + tile * 64 + vcc);
;     }
;   };
;   auto stage = [&](u32x4 (&rk)[2], u32x4 (&rv)[2], int buf) {
; #pragma unroll
;     for (int i = 0; i < 2; ++i) {
;       *(u32x4*)(sK0 + buf * 64 * 136 + (krow + 32 * i) * 136 + kcc) = rk[i];
;       *(u32x4*)(sV0 + buf * 128 * 72 + (vrow + 64 * i) * 72 + vcc) = rv[i];
;     }
;   };
;     ...
;   issue(0, rkA, rvA);
;   __syncthreads();
;   stage(rkA, rvA, 0);
;   issue(1, rkA, rvA);
;   issue(2, rkB, rvB);
;   __syncthreads();
	global_load_dwordx4 v[98:101], v[70:71], off
	global_load_dwordx4 v[114:117], v[32:33], off
	v_add_co_u32_e32 v32, vcc, s4, v30
	s_mov_b32 s4, 0xa000
	s_nop 0
	v_addc_co_u32_e32 v33, vcc, 0, v31, vcc
	global_load_dwordx4 v[106:109], v[28:29], off offset:128
	global_load_dwordx4 v[110:113], v[28:29], off offset:256
	v_add_co_u32_e32 v28, vcc, s4, v30
	v_max_f32_e32 v25, v25, v25
	s_nop 0
	v_addc_co_u32_e32 v29, vcc, 0, v31, vcc
	global_load_dwordx4 v[102:105], v[32:33], off
	global_load_dwordx4 v[118:121], v[28:29], off
	global_load_dwordx4 v[126:129], v[26:27], off offset:128
	global_load_dwordx4 v[122:125], v[26:27], off offset:256
	v_max_f32_e32 v21, v21, v25
	ds_bpermute_b32 v25, v75, v21
	v_max_f32_e32 v23, v23, v74
	ds_bpermute_b32 v26, v75, v23
	v_cmp_lt_i32_e32 vcc, v164, v158
	v_bfe_u32 v28, v72, 4, 2
	s_waitcnt lgkmcnt(1)
	v_max_f32_e32 v25, v25, v25
	v_max_f32_e32 v21, v21, v25
	s_waitcnt lgkmcnt(0)
	v_max_f32_e32 v25, v26, v26
	v_cndmask_b32_e32 v26, v157, v164, vcc
	v_lshlrev_b32_e32 v26, 2, v26
	ds_bpermute_b32 v27, v26, v21
	v_max_f32_e32 v23, v23, v25
	ds_bpermute_b32 v25, v26, v23
	v_lshlrev_b32_e32 v29, 3, v28
	s_mov_b32 s4, 0
	s_waitcnt lgkmcnt(1)
	v_max_f32_e32 v26, v27, v27
	v_max_f32_e32 v21, v21, v26
	s_waitcnt lgkmcnt(0)
	v_max_f32_e32 v25, v25, v25
	v_max_f32_e32 v23, v23, v25
	v_mul_f32_e32 v21, 0x413504f3, v21
	v_mul_f32_e32 v21, v21, v23
	v_lshrrev_b32_e32 v231, 2, v24
	v_lshrrev_b32_e32 v232, 3, v24
	v_xor_b32_e32 v231, v231, v232
	v_and_b32_e32 v231, 1, v231
	v_lshlrev_b32_e32 v231, 4, v231
	v_xor_b32_e32 v230, v20, v231
	v_mad_u64_u32 v[146:147], s[8:9], v24, s5, v[230:231]
	s_movk_i32 s5, 0x90
	v_mad_u64_u32 v[148:149], s[8:9], v77, s5, v[22:23]
	s_waitcnt vmcnt(17)
	ds_write_b128 v146, v[10:13]
	ds_write_b128 v148, v[2:5] offset:34816
	s_waitcnt vmcnt(14)
	ds_write_b128 v146, v[66:69] offset:8704
	ds_write_b128 v148, v[6:9] offset:44032
	v_mul_u32_u24_e32 v2, 0x88, v76
	v_lshlrev_b32_e32 v2, 1, v2
	v_lshrrev_b32_e32 v233, 2, v76
	v_lshrrev_b32_e32 v234, 3, v76
	v_xor_b32_e32 v233, v233, v234
	v_and_b32_e32 v233, 1, v233
	v_lshlrev_b32_e32 v233, 4, v233
	v_xor_b32_e32 v0, v0, v233
	v_add_u32_e32 v171, v2, v0
	v_mul_u32_u24_e32 v0, 0x48, v76
	v_lshl_add_u32 v0, v0, 1, v29
	v_mad_i64_i32 v[26:27], s[8:9], v77, s66, 0
	v_lshlrev_b32_e32 v3, 7, v76
	v_add_u32_e32 v173, 0x10600, v0
	v_add_u32_e32 v174, 0x10f00, v0
	v_add_u32_e32 v176, 0x10640, v0
	v_add_u32_e32 v177, 0x10f40, v0
	v_and_b32_e32 v0, 7, v72
	v_sub_u32_e32 v2, v2, v3
	v_lshl_or_b32 v26, v0, 4, v26
	v_add_u32_e32 v149, v2, v29
	v_lshl_add_u64 v[2:3], v[16:17], 0, v[26:27]
	s_mov_b64 s[8:9], 0x42200
	v_lshl_add_u64 v[150:151], v[2:3], 0, s[8:9]
	v_lshl_add_u64 v[2:3], v[14:15], 0, v[18:19]
	s_mov_b64 s[8:9], 0x12000
	v_mov_b32_e32 v4, v1
	v_mov_b32_e32 v5, v1
	v_mul_f32_e32 v170, 0x3fb8aa3b, v21
	v_lshlrev_b32_e32 v147, 2, v28
	v_lshl_add_u64 v[152:153], v[2:3], 0, s[8:9]
	v_mov_b32_e32 v0, v1
	v_mov_b32_e32 v2, v1
	v_mov_b32_e32 v3, v1
	v_mov_b64_e32 v[8:9], v[4:5]
	v_mov_b64_e32 v[12:13], v[4:5]
	v_mov_b64_e32 v[16:17], v[4:5]
	v_mov_b64_e32 v[20:21], v[4:5]
	v_mov_b64_e32 v[24:25], v[4:5]
	v_mov_b64_e32 v[28:29], v[4:5]
	v_mov_b64_e32 v[32:33], v[4:5]
	v_mov_b64_e32 v[68:69], v[4:5]
	v_mov_b64_e32 v[72:73], v[4:5]
	v_mov_b64_e32 v[76:77], v[4:5]
	v_mov_b64_e32 v[80:81], v[4:5]
	v_mov_b64_e32 v[84:85], v[4:5]
	v_mov_b64_e32 v[88:89], v[4:5]
	v_mov_b64_e32 v[92:93], v[4:5]
	v_mov_b64_e32 v[96:97], v[4:5]
	v_add_u32_e32 v172, 0xd000, v149
	v_add_u32_e32 v175, 0xd040, v149
	v_mov_b64_e32 v[6:7], v[2:3]
	v_mov_b64_e32 v[10:11], v[2:3]
	v_mov_b64_e32 v[14:15], v[2:3]
	v_mov_b64_e32 v[18:19], v[2:3]
	v_mov_b64_e32 v[22:23], v[2:3]
	v_mov_b64_e32 v[26:27], v[2:3]
	v_mov_b64_e32 v[30:31], v[2:3]
	v_mov_b64_e32 v[66:67], v[2:3]
	v_mov_b64_e32 v[70:71], v[2:3]
	v_mov_b64_e32 v[74:75], v[2:3]
	v_mov_b64_e32 v[78:79], v[2:3]
	v_mov_b64_e32 v[82:83], v[2:3]
	v_mov_b64_e32 v[86:87], v[2:3]
	v_mov_b64_e32 v[90:91], v[2:3]
	v_mov_b64_e32 v[94:95], v[2:3]
	v_mov_b64_e32 v[144:145], v[0:1]
	s_waitcnt lgkmcnt(0)
	s_barrier
	s_branch .LBB0_646
